# stack4 + FoX sample QK^T fragment double-buffering (wave-0 LDS reads under MFMAs)
# speedup vs baseline: 1.0204x; 1.0017x over previous
; __device__ __forceinline__ void qkt(f32x16& p0, f32x16& p1, const char* Ks, const char* Qs, int r32, int hi) {
; #pragma unroll
;     for (int d0 = 0; d0 < 8; ++d0) { const int cb = (d0 * 16 + hi * 8) * 2;
;         const bf16x8 qv = *reinterpret_cast<const bf16x8*>(Qs + KSWZ(r32, cb));
;         const bf16x8 b0 = *reinterpret_cast<const bf16x8*>(Ks + KSWZ(r32, cb));
;         const bf16x8 b1 = *reinterpret_cast<const bf16x8*>(Ks + KSWZ(32 + r32, cb));
;         p0 = __builtin_amdgcn_mfma_f32_32x32x16_bf16(b0, qv, p0, 0, 0, 0);
;         p1 = __builtin_amdgcn_mfma_f32_32x32x16_bf16(b1, qv, p1, 0, 0, 0); }
; }
.LBB0_615:
	v_cndmask_b32_e64 v66, 0, 1, s[74:75]
	s_cmp_lt_u32 s76, 8
	v_lshlrev_b32_e32 v0, 2, v152
	v_lshlrev_b32_e32 v164, 2, v154
	v_cmp_ne_u32_e64 s[0:1], 1, v66
	s_cbranch_scc0 .Lfsr_first_f1
	v_and_b32_e32 v76, 15, v183
	v_bfe_u32 v77, v183, 4, 3
	v_xor_b32_e32 v78, v76, v77
	v_lshrrev_b32_e32 v74, 1, v76
	v_xor_b32_e32 v74, v74, v77
	v_sub_u32_e32 v74, v74, v78
	v_and_b32_e32 v78, 1, v76
	v_lshlrev_b32_e32 v74, 4, v74
	v_lshl_add_u32 v74, v78, 3, v74
	v_lshrrev_b32_e32 v75, 3, v76
	v_lshrrev_b32_e32 v78, 2, v76
	v_sub_u32_e32 v75, v75, v78
	v_lshlrev_b32_e32 v75, 9, v75
	v_and_b32_e32 v78, 7, v76
	v_lshl_add_u32 v75, v78, 3, v75
	v_and_b32_e32 v78, 3, v76
	v_lshlrev_b32_e32 v78, 4, v78
	v_sub_u32_e32 v75, v75, v78
	v_add_u32_e32 v70, v133, v74
	v_add_u32_e32 v71, v198, v74
	v_add_u32_e32 v72, v199, v75
	v_add_u32_e32 v73, v200, v75
	s_waitcnt vmcnt(6)
	v_cvt_pk_bf16_f32 v66, v102, v103
	v_cvt_pk_bf16_f32 v67, v104, v105
	v_cvt_pk_bf16_f32 v68, v98, v99
	v_cvt_pk_bf16_f32 v69, v100, v101
	ds_write_b64 v70, v[66:67] offset:16384
	ds_write_b64 v70, v[68:69] offset:16512
	s_waitcnt vmcnt(4)
	v_cvt_pk_bf16_f32 v66, v110, v111
	v_cvt_pk_bf16_f32 v67, v112, v113
	v_cvt_pk_bf16_f32 v68, v106, v107
	v_cvt_pk_bf16_f32 v69, v108, v109
	ds_write_b64 v71, v[66:67] offset:16384
	ds_write_b64 v71, v[68:69] offset:16512
	s_waitcnt vmcnt(2)
	v_cvt_pk_bf16_f32 v66, v122, v123
	v_cvt_pk_bf16_f32 v67, v124, v125
	v_cvt_pk_bf16_f32 v68, v114, v115
	v_cvt_pk_bf16_f32 v69, v116, v117
	ds_write_b64 v72, v[66:67] offset:49152
	ds_write_b64 v72, v[68:69] offset:50176
	s_waitcnt vmcnt(0)
	v_cvt_pk_bf16_f32 v66, v126, v127
	v_cvt_pk_bf16_f32 v67, v128, v129
	v_cvt_pk_bf16_f32 v68, v118, v119
	v_cvt_pk_bf16_f32 v69, v120, v121
	ds_write_b64 v73, v[66:67] offset:49152
	ds_write_b64 v73, v[68:69] offset:50176
	v_or_b32_e32 v67, s11, v171
	v_or_b32_e32 v66, s3, v170
	v_readlane_b32 s36, v253, 16
	v_lshlrev_b64 v[66:67], 2, v[66:67]
	v_and_b32_e32 v72, 15, v183
	v_lshlrev_b32_e32 v72, 4, v72
	v_sub_u32_e32 v66, v66, v72
	v_readlane_b32 s40, v253, 20
	v_readlane_b32 s41, v253, 21
	v_readlane_b32 s42, v253, 22
	v_readlane_b32 s43, v253, 23
	v_lshl_add_u64 v[68:69], s[40:41], 0, v[66:67]
	v_mov_b32_e32 v165, v1
	v_lshl_add_u64 v[70:71], v[68:69], 0, v[0:1]
	v_lshl_add_u64 v[68:69], v[68:69], 0, v[164:165]
	v_lshl_add_u64 v[66:67], s[42:43], 0, v[66:67]
	global_load_dwordx4 v[98:101], v[70:71], off offset:256 nt
	global_load_dwordx4 v[102:105], v[70:71], off nt
	global_load_dwordx4 v[106:109], v[68:69], off offset:256 nt
	global_load_dwordx4 v[110:113], v[68:69], off nt
	v_lshl_add_u64 v[68:69], v[66:67], 0, v[0:1]
	v_lshl_add_u64 v[66:67], v[66:67], 0, v[164:165]
	global_load_dwordx4 v[114:117], v[68:69], off offset:256 nt
	global_load_dwordx4 v[122:125], v[68:69], off nt
	global_load_dwordx4 v[118:121], v[66:67], off offset:256 nt
	global_load_dwordx4 v[126:129], v[66:67], off nt
	s_and_b64 vcc, exec, s[0:1]
	v_readlane_b32 s37, v253, 17
	v_readlane_b32 s38, v253, 18
	v_readlane_b32 s39, v253, 19
	v_readlane_b32 s44, v253, 24
	v_readlane_b32 s45, v253, 25
	v_readlane_b32 s46, v253, 26
	v_readlane_b32 s47, v253, 27
	v_readlane_b32 s48, v253, 28
	v_readlane_b32 s49, v253, 29
	v_readlane_b32 s50, v253, 30
	v_readlane_b32 s51, v253, 31
	s_waitcnt lgkmcnt(0)
	s_barrier
	s_cbranch_vccnz .LBB0_622
	v_add_u32_e32 v78, s97, v214
	v_add_u32_e32 v66, 0x11100, v78
	v_add_u32_e32 v67, 0x11180, v78
	v_add_u32_e32 v70, 0x11120, v78
	v_add_u32_e32 v74, 0x11140, v78
	ds_read_b128 v[82:85], v66
	ds_read_b128 v[66:69], v67
	ds_read_b128 v[86:89], v70
	ds_read_b128 v[90:93], v74
	v_add_u32_e32 v70, 0x111a0, v78
	v_add_u32_e32 v74, 0x111c0, v78
	v_add_u32_e32 v79, 0x11160, v78
	v_add_u32_e32 v78, 0x111e0, v78
	ds_read_b128 v[94:97], v79
	ds_read_b128 v[78:81], v78
	ds_read_b128 v[70:73], v70
	ds_read_b128 v[74:77], v74
	v_add_u32_e32 v165, s33, v182
	ds_read_b128 v[202:205], v165
	ds_read_b128 v[206:209], v182 offset:16384
	ds_read_b128 v[216:219], v182 offset:24576
	v_add_u32_e32 v165, s33, v184
	ds_read_b128 v[234:237], v165
	ds_read_b128 v[238:241], v184 offset:16384
	ds_read_b128 v[242:245], v184 offset:24576
	s_waitcnt lgkmcnt(4)
	v_mfma_f32_32x32x16_bf16 v[82:97], v[206:209], v[202:205], v[82:97]
	s_waitcnt lgkmcnt(3)
	v_mfma_f32_32x32x16_bf16 v[66:81], v[216:219], v[202:205], v[66:81]
	v_add_u32_e32 v165, s33, v185
	ds_read_b128 v[202:205], v165
	ds_read_b128 v[206:209], v185 offset:16384
	ds_read_b128 v[216:219], v185 offset:24576
	s_waitcnt lgkmcnt(4)
	v_mfma_f32_32x32x16_bf16 v[82:97], v[238:241], v[234:237], v[82:97]
	s_waitcnt lgkmcnt(3)
	v_mfma_f32_32x32x16_bf16 v[66:81], v[242:245], v[234:237], v[66:81]
	v_add_u32_e32 v165, s33, v186
	ds_read_b128 v[234:237], v165
	ds_read_b128 v[238:241], v186 offset:16384
	ds_read_b128 v[242:245], v186 offset:24576
	s_waitcnt lgkmcnt(4)
	v_mfma_f32_32x32x16_bf16 v[82:97], v[206:209], v[202:205], v[82:97]
	s_waitcnt lgkmcnt(3)
	v_mfma_f32_32x32x16_bf16 v[66:81], v[216:219], v[202:205], v[66:81]
	v_add_u32_e32 v165, s33, v187
	ds_read_b128 v[202:205], v165
	ds_read_b128 v[206:209], v187 offset:16384
	ds_read_b128 v[216:219], v187 offset:24576
	s_waitcnt lgkmcnt(4)
	v_mfma_f32_32x32x16_bf16 v[82:97], v[238:241], v[234:237], v[82:97]
	s_waitcnt lgkmcnt(3)
	v_mfma_f32_32x32x16_bf16 v[66:81], v[242:245], v[234:237], v[66:81]
	v_add_u32_e32 v165, s33, v188
	ds_read_b128 v[234:237], v165
	ds_read_b128 v[238:241], v188 offset:16384
	ds_read_b128 v[242:245], v188 offset:24576
	s_waitcnt lgkmcnt(4)
	v_mfma_f32_32x32x16_bf16 v[82:97], v[206:209], v[202:205], v[82:97]
	s_waitcnt lgkmcnt(3)
; __device__ __forceinline__ int crow(int r, int hi) { return (r & 3) + 8 * (r >> 2) + 4 * hi; }
; __device__ __forceinline__ void qkt(f32x16& p0, f32x16& p1, const char* Ks, const char* Qs, int r32, int hi) {
; #pragma unroll
;     for (int d0 = 0; d0 < 8; ++d0) { const int cb = (d0 * 16 + hi * 8) * 2;
;         const bf16x8 qv = *reinterpret_cast<const bf16x8*>(Qs + KSWZ(r32, cb));
;         const bf16x8 b0 = *reinterpret_cast<const bf16x8*>(Ks + KSWZ(r32, cb));
;         const bf16x8 b1 = *reinterpret_cast<const bf16x8*>(Ks + KSWZ(32 + r32, cb));
;         p0 = __builtin_amdgcn_mfma_f32_32x32x16_bf16(b0, qv, p0, 0, 0, 0);
;         p1 = __builtin_amdgcn_mfma_f32_32x32x16_bf16(b1, qv, p1, 0, 0, 0); }
; }
; template <int MODE, bool SAMPLE>
; __device__ __forceinline__ void attn_unit(const Params& p, char* lds, int b, int h, int qb) {
;     ...
;                 float pmax = p0[0];
; #pragma unroll
;                 for (int r = 1; r < 16; ++r) pmax = fmaxf(pmax, p0[r]);
; #pragma unroll
;                 for (int r = 0; r < 16; ++r) pmax = fmaxf(pmax, p1[r]);
;                 { auto rr = __builtin_amdgcn_permlane32_swap(__float_as_uint(pmax), __float_as_uint(pmax), false, false); pmax = fmaxf(__uint_as_float(rr[0]), __uint_as_float(rr[1])); }
;                 float alpha = 1.f;
;                 if (!__all(pmax - m_reg <= 8.f)) { const float mn = fmaxf(m_reg, pmax); alpha = __builtin_amdgcn_exp2f(m_reg - mn); m_reg = mn; }
;                 float ps = 0.f;
; #pragma unroll
;                 for (int r = 0; r < 16; ++r) { p0[r] = __builtin_amdgcn_exp2f(p0[r] - m_reg); p1[r] = __builtin_amdgcn_exp2f(p1[r] - m_reg); ps += p0[r] + p1[r]; }
;                 { auto rr = __builtin_amdgcn_permlane32_swap(__float_as_uint(ps), __float_as_uint(ps), false, false); ps = __uint_as_float(rr[0]) + __uint_as_float(rr[1]); }
;                 l_reg = l_reg * alpha + ps;
;                 if (__any(alpha < 1.f)) { if (hi == 0) wsc[r32] = alpha; asm volatile("s_waitcnt lgkmcnt(0)" ::: "memory");
; #pragma unroll
;                     for (int d = 0; d < 4; ++d)
; #pragma unroll
;                         for (int r = 0; r < 16; ++r) o[d][r] *= wsc[crow(r, hi)]; }
	v_mfma_f32_32x32x16_bf16 v[66:81], v[216:219], v[202:205], v[66:81]
	v_add_u32_e32 v165, s33, v189
	ds_read_b128 v[202:205], v165
	ds_read_b128 v[206:209], v189 offset:16384
	ds_read_b128 v[216:219], v189 offset:24576
	s_waitcnt lgkmcnt(4)
	v_mfma_f32_32x32x16_bf16 v[82:97], v[238:241], v[234:237], v[82:97]
	s_waitcnt lgkmcnt(3)
	v_mfma_f32_32x32x16_bf16 v[66:81], v[242:245], v[234:237], v[66:81]
	v_add_u32_e32 v165, s33, v190
	ds_read_b128 v[234:237], v165
	ds_read_b128 v[238:241], v190 offset:16384
	ds_read_b128 v[242:245], v190 offset:24576
	s_waitcnt lgkmcnt(4)
	v_mfma_f32_32x32x16_bf16 v[82:97], v[206:209], v[202:205], v[82:97]
	s_waitcnt lgkmcnt(3)
	v_mfma_f32_32x32x16_bf16 v[66:81], v[216:219], v[202:205], v[66:81]
	s_waitcnt lgkmcnt(1)
	v_mfma_f32_32x32x16_bf16 v[82:97], v[238:241], v[234:237], v[82:97]
	s_waitcnt lgkmcnt(0)
	v_mfma_f32_32x32x16_bf16 v[66:81], v[242:245], v[234:237], v[66:81]
	s_nop 1
	s_nop 9
	v_max_f32_e32 v165, v83, v83
	v_max_f32_e32 v202, v82, v82
	v_max_f32_e32 v165, v202, v165
	v_max3_f32 v165, v165, v84, v85
	v_max3_f32 v165, v165, v86, v87
	v_max3_f32 v165, v165, v88, v89
	v_max3_f32 v165, v165, v90, v91
	v_max3_f32 v165, v165, v92, v93
	v_max3_f32 v165, v165, v94, v95
	v_max3_f32 v165, v165, v96, v97
	v_max3_f32 v165, v165, v66, v67
	v_max3_f32 v165, v165, v68, v69
	v_max3_f32 v165, v165, v70, v71
	v_max3_f32 v165, v165, v72, v73
	v_max3_f32 v165, v165, v74, v75
	v_max3_f32 v165, v165, v76, v77
	v_max3_f32 v165, v165, v78, v79
	v_max3_f32 v165, v165, v80, v81
	v_mov_b32_e32 v202, v165
	s_nop 1
	v_permlane32_swap_b32_e32 v165, v202
	v_max_f32_e32 v202, v202, v202
	v_max_f32_e32 v165, v165, v165
	v_max_f32_e32 v165, v165, v202
	v_sub_f32_e32 v202, v165, v163
	v_cmp_ge_f32_e32 vcc, s83, v202
	s_cmp_eq_u64 vcc, exec
	v_max_f32_e32 v202, v163, v163
	s_cselect_b64 vcc, -1, 0
	v_max_f32_e32 v165, v202, v165
	v_sub_f32_e32 v202, v163, v165
	v_cndmask_b32_e32 v163, v165, v163, vcc
	v_sub_f32_e32 v82, v82, v163
	v_sub_f32_e32 v66, v66, v163
	v_exp_f32_e32 v165, v82
	v_exp_f32_e32 v82, v66
	v_exp_f32_e32 v203, v202
	v_sub_f32_e32 v67, v67, v163
	v_sub_f32_e32 v68, v68, v163
	v_add_f32_e32 v66, v165, v82
	v_add_f32_e32 v202, 0, v66
	v_sub_f32_e32 v66, v83, v163
	v_exp_f32_e32 v66, v66
	v_exp_f32_e32 v83, v67
	v_sub_f32_e32 v69, v69, v163
	v_sub_f32_e32 v70, v70, v163
	v_exp_f32_e32 v70, v70
	v_add_f32_e32 v67, v66, v83
	v_add_f32_e32 v202, v67, v202
	v_sub_f32_e32 v67, v84, v163
	v_exp_f32_e32 v67, v67
	v_exp_f32_e32 v84, v68
	v_sub_f32_e32 v71, v71, v163
	v_exp_f32_e32 v71, v71
	v_sub_f32_e32 v72, v72, v163
	v_add_f32_e32 v68, v67, v84
	v_add_f32_e32 v202, v68, v202
	v_sub_f32_e32 v68, v85, v163
	v_exp_f32_e32 v68, v68
	v_exp_f32_e32 v85, v69
	v_exp_f32_e32 v72, v72
	v_sub_f32_e32 v73, v73, v163
	v_exp_f32_e32 v73, v73
	v_add_f32_e32 v69, v68, v85
	v_add_f32_e32 v202, v69, v202
	v_sub_f32_e32 v69, v86, v163
	v_exp_f32_e32 v69, v69
	v_sub_f32_e32 v74, v74, v163
	v_exp_f32_e32 v74, v74
	v_sub_f32_e32 v75, v75, v163
	v_add_f32_e32 v86, v69, v70
	v_add_f32_e32 v202, v86, v202
	v_sub_f32_e32 v86, v87, v163
	v_exp_f32_e32 v86, v86
	v_exp_f32_e32 v75, v75
	v_sub_f32_e32 v76, v76, v163
	v_exp_f32_e32 v76, v76
	v_add_f32_e32 v87, v86, v71
	v_add_f32_e32 v202, v87, v202
	v_sub_f32_e32 v87, v88, v163
	v_exp_f32_e32 v87, v87
	v_sub_f32_e32 v77, v77, v163
	v_exp_f32_e32 v77, v77
	v_sub_f32_e32 v78, v78, v163
	v_add_f32_e32 v88, v87, v72
	v_add_f32_e32 v202, v88, v202
	v_sub_f32_e32 v88, v89, v163
	v_exp_f32_e32 v88, v88
	v_exp_f32_e32 v78, v78
	v_sub_f32_e32 v79, v79, v163
	v_exp_f32_e32 v79, v79
	v_add_f32_e32 v89, v88, v73
	v_add_f32_e32 v202, v89, v202
	v_sub_f32_e32 v89, v90, v163
	v_exp_f32_e32 v89, v89
	v_sub_f32_e32 v80, v80, v163
	v_exp_f32_e32 v80, v80
	v_sub_f32_e32 v81, v81, v163
	v_add_f32_e32 v90, v89, v74
	v_add_f32_e32 v202, v90, v202
	v_sub_f32_e32 v90, v91, v163
	v_exp_f32_e32 v90, v90
	v_exp_f32_e32 v81, v81
	v_add_f32_e32 v91, v90, v75
	v_add_f32_e32 v202, v91, v202
	v_sub_f32_e32 v91, v92, v163
	v_exp_f32_e32 v91, v91
	s_nop 0
	v_add_f32_e32 v92, v91, v76
	v_add_f32_e32 v202, v92, v202
	v_sub_f32_e32 v92, v93, v163
	v_exp_f32_e32 v92, v92
	s_nop 0
	v_add_f32_e32 v93, v92, v77
	v_add_f32_e32 v202, v93, v202
	v_sub_f32_e32 v93, v94, v163
	v_exp_f32_e32 v93, v93
	s_nop 0
	v_add_f32_e32 v94, v93, v78
	v_add_f32_e32 v202, v94, v202
	v_sub_f32_e32 v94, v95, v163
	v_exp_f32_e32 v94, v94
	s_nop 0
	v_add_f32_e32 v95, v94, v79
	v_add_f32_e32 v202, v95, v202
	v_sub_f32_e32 v95, v96, v163
	v_exp_f32_e32 v95, v95
	s_nop 0
	v_add_f32_e32 v96, v95, v80
	v_add_f32_e32 v202, v96, v202
	v_sub_f32_e32 v96, v97, v163
	v_exp_f32_e32 v96, v96
	s_nop 0
	v_add_f32_e32 v97, v96, v81
	v_add_f32_e32 v202, v97, v202
	v_cndmask_b32_e64 v97, v203, 1.0, vcc
	v_mov_b32_e32 v203, v202
	s_nop 1
	v_permlane32_swap_b32_e32 v202, v203
	v_cmp_gt_f32_e32 vcc, 1.0, v97
	s_cbranch_vccz .LBB0_621
	s_and_saveexec_b64 s[4:5], s[14:15]
	ds_write_b32 v145, v97
	s_or_b64 exec, exec, s[4:5]
	s_waitcnt lgkmcnt(0)
	ds_read_b128 v[204:207], v147 offset:96
	ds_read_b128 v[216:219], v147 offset:64
	ds_read_b128 v[220:223], v147 offset:32
	ds_read_b128 v[224:227], v147
	s_waitcnt lgkmcnt(3)
	v_pk_mul_f32 v[64:65], v[64:65], v[206:207]
	s_waitcnt lgkmcnt(2)
	v_pk_mul_f32 v[60:61], v[60:61], v[218:219]
	s_waitcnt lgkmcnt(1)
	v_pk_mul_f32 v[56:57], v[56:57], v[222:223]
	s_waitcnt lgkmcnt(0)
	v_pk_mul_f32 v[52:53], v[52:53], v[226:227]
	v_pk_mul_f32 v[62:63], v[62:63], v[204:205]
	v_pk_mul_f32 v[58:59], v[58:59], v[216:217]
	v_pk_mul_f32 v[54:55], v[54:55], v[220:221]
	v_pk_mul_f32 v[50:51], v[50:51], v[224:225]
	v_pk_mul_f32 v[48:49], v[48:49], v[206:207]
	v_pk_mul_f32 v[44:45], v[44:45], v[218:219]
	v_pk_mul_f32 v[40:41], v[40:41], v[222:223]
	v_pk_mul_f32 v[36:37], v[36:37], v[226:227]
	v_pk_mul_f32 v[46:47], v[46:47], v[204:205]
	v_pk_mul_f32 v[42:43], v[42:43], v[216:217]
	v_pk_mul_f32 v[38:39], v[38:39], v[220:221]
	v_pk_mul_f32 v[34:35], v[34:35], v[224:225]
	v_pk_mul_f32 v[32:33], v[32:33], v[206:207]
	v_pk_mul_f32 v[28:29], v[28:29], v[218:219]
	v_pk_mul_f32 v[24:25], v[24:25], v[222:223]
	v_pk_mul_f32 v[20:21], v[20:21], v[226:227]
	v_pk_mul_f32 v[30:31], v[30:31], v[204:205]
	v_pk_mul_f32 v[26:27], v[26:27], v[216:217]
	v_pk_mul_f32 v[22:23], v[22:23], v[220:221]
	v_pk_mul_f32 v[18:19], v[18:19], v[224:225]
	v_pk_mul_f32 v[16:17], v[16:17], v[206:207]
	v_pk_mul_f32 v[12:13], v[12:13], v[218:219]
	v_pk_mul_f32 v[8:9], v[8:9], v[222:223]
	v_pk_mul_f32 v[4:5], v[4:5], v[226:227]
	v_pk_mul_f32 v[14:15], v[14:15], v[204:205]
	v_pk_mul_f32 v[10:11], v[10:11], v[216:217]
	v_pk_mul_f32 v[6:7], v[6:7], v[220:221]
	v_pk_mul_f32 v[2:3], v[2:3], v[224:225]

; __device__ __forceinline__ int crow(int r, int hi) { return (r & 3) + 8 * (r >> 2) + 4 * hi; }
; __device__ __forceinline__ void qkt(f32x16& p0, f32x16& p1, const char* Ks, const char* Qs, int r32, int hi) {
; #pragma unroll
;     for (int d0 = 0; d0 < 8; ++d0) { const int cb = (d0 * 16 + hi * 8) * 2;
;         const bf16x8 qv = *reinterpret_cast<const bf16x8*>(Qs + KSWZ(r32, cb));
;         const bf16x8 b0 = *reinterpret_cast<const bf16x8*>(Ks + KSWZ(r32, cb));
;         const bf16x8 b1 = *reinterpret_cast<const bf16x8*>(Ks + KSWZ(32 + r32, cb));
;         p0 = __builtin_amdgcn_mfma_f32_32x32x16_bf16(b0, qv, p0, 0, 0, 0);
;         p1 = __builtin_amdgcn_mfma_f32_32x32x16_bf16(b1, qv, p1, 0, 0, 0); }
; }
; template <int MODE, bool SAMPLE>
; __device__ __forceinline__ void attn_unit(const Params& p, char* lds, int b, int h, int qb) {
;     ...
;             const char* Kt = K_lds + buf * 16384; const int vb = vb0 + buf * 16384;
;             f32x16 p0, p1; bf16x8 pa0, pa1, pa2, pa3;
;             if (MODE == 0) {
;                 const float* bt = biasL + j * 64 + 4 * hi;
; #pragma unroll
;                 for (int g = 0; g < 4; ++g) { const f32x4 a = *(const f32x4*)(bt + 8 * g), c = *(const f32x4*)(bt + 32 + 8 * g);
; #pragma unroll
;                     for (int i = 0; i < 4; ++i) { p0[4 * g + i] = a[i]; p1[4 * g + i] = c[i]; } }
;                 qkt(p0, p1, Kt, Qs, r32, hi);
;                 if (j == jd) {
; #pragma unroll
;                     for (int r = 0; r < 16; ++r) { const int kp = j * 64 + crow(r, hi); if (kp > qpos) p0[r] = -1e30f; if (kp + 32 > qpos) p1[r] = -1e30f; } }
.LBB0_624:
	s_and_b64 vcc, exec, s[0:1]
	v_add_u32_e32 v202, 0, v182
	v_add_u32_e32 v203, 0, v184
	v_add_u32_e32 v204, 0, v185
	v_add_u32_e32 v205, 0, v186
	v_add_u32_e32 v206, 0, v187
	v_add_u32_e32 v207, 0, v188
	v_add_u32_e32 v208, 0, v189
	v_add_u32_e32 v209, 0, v190
	s_waitcnt lgkmcnt(0)
	s_barrier
	s_cbranch_vccnz .LBB0_614
	v_add_u32_e32 v94, s97, v214
	v_add_u32_e32 v66, 0x11000, v94
	v_add_u32_e32 v70, 0x11080, v94
	ds_read_b128 v[66:69], v66
	ds_read_b128 v[82:85], v70
	v_add_u32_e32 v70, 0x11020, v94
	v_add_u32_e32 v74, 0x11040, v94
	v_add_u32_e32 v78, 0x11060, v94
	ds_read_b128 v[70:73], v70
	ds_read_b128 v[74:77], v74
	ds_read_b128 v[78:81], v78
	v_add_u32_e32 v86, 0x110a0, v94
	v_add_u32_e32 v95, 0x110c0, v94
	v_add_u32_e32 v94, 0x110e0, v94
	ds_read_b128 v[86:89], v86
	ds_read_b128 v[90:93], v95
	ds_read_b128 v[94:97], v94
	s_cmp_lg_u32 s97, 0
	v_add_u32_e32 v165, s33, v182
	ds_read_b128 v[220:223], v165
	ds_read_b128 v[216:219], v202
	ds_read_b128 v[246:249], v202 offset:8192
	v_add_u32_e32 v165, s33, v184
	ds_read_b128 v[234:237], v165
	ds_read_b128 v[238:241], v203
	ds_read_b128 v[242:245], v203 offset:8192
	s_waitcnt lgkmcnt(4)
	v_mfma_f32_32x32x16_bf16 v[66:81], v[216:219], v[220:223], v[66:81]
	s_waitcnt lgkmcnt(3)
	v_mfma_f32_32x32x16_bf16 v[82:97], v[246:249], v[220:223], v[82:97]
	v_add_u32_e32 v165, s33, v185
	ds_read_b128 v[220:223], v165
	ds_read_b128 v[216:219], v204
	ds_read_b128 v[246:249], v204 offset:8192
	s_waitcnt lgkmcnt(4)
	v_mfma_f32_32x32x16_bf16 v[66:81], v[238:241], v[234:237], v[66:81]
	s_waitcnt lgkmcnt(3)
	v_mfma_f32_32x32x16_bf16 v[82:97], v[242:245], v[234:237], v[82:97]
	v_add_u32_e32 v165, s33, v186
	ds_read_b128 v[234:237], v165
	ds_read_b128 v[238:241], v205
	ds_read_b128 v[242:245], v205 offset:8192
	s_waitcnt lgkmcnt(4)
	v_mfma_f32_32x32x16_bf16 v[66:81], v[216:219], v[220:223], v[66:81]
	s_waitcnt lgkmcnt(3)
	v_mfma_f32_32x32x16_bf16 v[82:97], v[246:249], v[220:223], v[82:97]
	v_add_u32_e32 v165, s33, v187
	ds_read_b128 v[220:223], v165
	ds_read_b128 v[216:219], v206
	ds_read_b128 v[246:249], v206 offset:8192
	s_waitcnt lgkmcnt(4)
	v_mfma_f32_32x32x16_bf16 v[66:81], v[238:241], v[234:237], v[66:81]
	s_waitcnt lgkmcnt(3)
	v_mfma_f32_32x32x16_bf16 v[82:97], v[242:245], v[234:237], v[82:97]
	v_add_u32_e32 v165, s33, v188
	ds_read_b128 v[234:237], v165
	ds_read_b128 v[238:241], v207
	ds_read_b128 v[242:245], v207 offset:8192
	s_waitcnt lgkmcnt(4)
	v_mfma_f32_32x32x16_bf16 v[66:81], v[216:219], v[220:223], v[66:81]
	s_waitcnt lgkmcnt(3)
	v_mfma_f32_32x32x16_bf16 v[82:97], v[246:249], v[220:223], v[82:97]
	v_add_u32_e32 v165, s33, v189
	ds_read_b128 v[220:223], v165
	ds_read_b128 v[216:219], v208
	ds_read_b128 v[246:249], v208 offset:8192
	s_waitcnt lgkmcnt(4)
	v_mfma_f32_32x32x16_bf16 v[66:81], v[238:241], v[234:237], v[66:81]
	s_waitcnt lgkmcnt(3)
	v_mfma_f32_32x32x16_bf16 v[82:97], v[242:245], v[234:237], v[82:97]
	v_add_u32_e32 v165, s33, v190
	ds_read_b128 v[234:237], v165
	ds_read_b128 v[238:241], v209
	ds_read_b128 v[242:245], v209 offset:8192
	s_waitcnt lgkmcnt(4)
	v_mfma_f32_32x32x16_bf16 v[66:81], v[216:219], v[220:223], v[66:81]
	s_waitcnt lgkmcnt(3)
	v_mfma_f32_32x32x16_bf16 v[82:97], v[246:249], v[220:223], v[82:97]
	s_waitcnt lgkmcnt(1)
	v_mfma_f32_32x32x16_bf16 v[66:81], v[238:241], v[234:237], v[66:81]
	s_waitcnt lgkmcnt(0)
	v_mfma_f32_32x32x16_bf16 v[82:97], v[242:245], v[234:237], v[82:97]
	s_nop 1
	s_cbranch_scc1 .LBB0_627
	s_nop 10
	v_mov_b32_e32 v82, 0xf149f2ca
	v_cndmask_b32_e64 v74, v66, v82, s[22:23]
	v_cndmask_b32_e64 v66, v74, v66, s[24:25]
	v_cndmask_b32_e64 v67, v82, v67, s[24:25]
	v_cndmask_b32_e64 v68, v68, v82, s[26:27]
	v_cndmask_b32_e64 v69, v69, v82, s[28:29]
	v_cndmask_b32_e64 v70, v70, v82, s[30:31]
	v_cndmask_b32_e64 v71, v71, v82, s[34:35]
	v_cndmask_b32_e64 v72, v72, v82, s[16:17]
	v_cndmask_b32_e64 v73, v73, v82, s[88:89]
	v_mov_b32_e32 v83, v82
	v_mov_b32_e32 v84, v82
	v_mov_b32_e32 v85, v82
	v_mov_b32_e32 v86, v82
	v_mov_b32_e32 v87, v82
	v_mov_b32_e32 v88, v82
	v_mov_b32_e32 v89, v82
	v_mov_b32_e32 v90, v82
	v_mov_b32_e32 v91, v82
	v_mov_b32_e32 v92, v82
	v_mov_b32_e32 v93, v82
	v_mov_b32_e32 v94, v82
	v_mov_b32_e32 v95, v82
	v_mov_b32_e32 v96, v82
	v_mov_b32_e32 v97, v82
	v_mov_b32_e32 v74, v82
	v_mov_b32_e32 v75, v82
	v_mov_b32_e32 v76, v82
	v_mov_b32_e32 v77, v82
	v_mov_b32_e32 v78, v82
	v_mov_b32_e32 v79, v82
	v_mov_b32_e32 v80, v82
	v_mov_b32_e32 v81, v82

; __device__ __forceinline__ void qkt(f32x16& p0, f32x16& p1, const char* Ks, const char* Qs, int r32, int hi) {
; #pragma unroll
;     for (int d0 = 0; d0 < 8; ++d0) { const int cb = (d0 * 16 + hi * 8) * 2;
;         const bf16x8 qv = *reinterpret_cast<const bf16x8*>(Qs + KSWZ(r32, cb));
;         const bf16x8 b0 = *reinterpret_cast<const bf16x8*>(Ks + KSWZ(r32, cb));
;         const bf16x8 b1 = *reinterpret_cast<const bf16x8*>(Ks + KSWZ(32 + r32, cb));
;         p0 = __builtin_amdgcn_mfma_f32_32x32x16_bf16(b0, qv, p0, 0, 0, 0);
;         p1 = __builtin_amdgcn_mfma_f32_32x32x16_bf16(b1, qv, p1, 0, 0, 0); }
; }
.LBB0_844:
	v_cndmask_b32_e64 v66, 0, 1, s[74:75]
	s_cmp_lt_u32 s55, 8
	v_lshlrev_b32_e32 v0, 2, v150
	v_lshlrev_b32_e32 v162, 2, v152
	v_cmp_ne_u32_e64 s[0:1], 1, v66
	s_cbranch_scc0 .Lfsr_first_f2
	v_and_b32_e32 v76, 15, v183
	v_bfe_u32 v77, v183, 4, 3
	v_xor_b32_e32 v78, v76, v77
	v_lshrrev_b32_e32 v74, 1, v76
	v_xor_b32_e32 v74, v74, v77
	v_sub_u32_e32 v74, v74, v78
	v_and_b32_e32 v78, 1, v76
	v_lshlrev_b32_e32 v74, 4, v74
	v_lshl_add_u32 v74, v78, 3, v74
	v_lshrrev_b32_e32 v75, 3, v76
	v_lshrrev_b32_e32 v78, 2, v76
	v_sub_u32_e32 v75, v75, v78
	v_lshlrev_b32_e32 v75, 9, v75
	v_and_b32_e32 v78, 7, v76
	v_lshl_add_u32 v75, v78, 3, v75
	v_and_b32_e32 v78, 3, v76
	v_lshlrev_b32_e32 v78, 4, v78
	v_sub_u32_e32 v75, v75, v78
	v_add_u32_e32 v70, v198, v74
	v_add_u32_e32 v71, v199, v74
	v_add_u32_e32 v72, v200, v75
	v_add_u32_e32 v73, v201, v75
	s_waitcnt vmcnt(6)
	v_cvt_pk_bf16_f32 v66, v102, v103
	v_cvt_pk_bf16_f32 v67, v104, v105
	v_cvt_pk_bf16_f32 v68, v98, v99
	v_cvt_pk_bf16_f32 v69, v100, v101
	ds_write_b64 v70, v[66:67] offset:16384
	ds_write_b64 v70, v[68:69] offset:16512
	s_waitcnt vmcnt(4)
	v_cvt_pk_bf16_f32 v66, v110, v111
	v_cvt_pk_bf16_f32 v67, v112, v113
	v_cvt_pk_bf16_f32 v68, v106, v107
	v_cvt_pk_bf16_f32 v69, v108, v109
	ds_write_b64 v71, v[66:67] offset:16384
	ds_write_b64 v71, v[68:69] offset:16512
	s_waitcnt vmcnt(2)
	v_cvt_pk_bf16_f32 v66, v122, v123
	v_cvt_pk_bf16_f32 v67, v124, v125
	v_cvt_pk_bf16_f32 v68, v114, v115
	v_cvt_pk_bf16_f32 v69, v116, v117
	ds_write_b64 v72, v[66:67] offset:49152
	ds_write_b64 v72, v[68:69] offset:50176
	s_waitcnt vmcnt(0)
	v_cvt_pk_bf16_f32 v66, v126, v127
	v_cvt_pk_bf16_f32 v67, v128, v129
	v_cvt_pk_bf16_f32 v68, v118, v119
	v_cvt_pk_bf16_f32 v69, v120, v121
	ds_write_b64 v73, v[66:67] offset:49152
	ds_write_b64 v73, v[68:69] offset:50176
	v_or_b32_e32 v67, s61, v169
	v_or_b32_e32 v66, s9, v168
	v_readlane_b32 s36, v253, 16
	v_lshlrev_b64 v[66:67], 2, v[66:67]
	v_and_b32_e32 v72, 15, v183
	v_lshlrev_b32_e32 v72, 4, v72
	v_sub_u32_e32 v66, v66, v72
	v_readlane_b32 s40, v253, 20
	v_readlane_b32 s41, v253, 21
	v_readlane_b32 s42, v253, 22
	v_readlane_b32 s43, v253, 23
	v_lshl_add_u64 v[68:69], s[40:41], 0, v[66:67]
	v_mov_b32_e32 v163, v1
	v_lshl_add_u64 v[70:71], v[68:69], 0, v[0:1]
	v_lshl_add_u64 v[68:69], v[68:69], 0, v[162:163]
	v_lshl_add_u64 v[66:67], s[42:43], 0, v[66:67]
	global_load_dwordx4 v[98:101], v[70:71], off offset:256 nt
	global_load_dwordx4 v[102:105], v[70:71], off nt
	global_load_dwordx4 v[106:109], v[68:69], off offset:256 nt
	global_load_dwordx4 v[110:113], v[68:69], off nt
	v_lshl_add_u64 v[68:69], v[66:67], 0, v[0:1]
	v_lshl_add_u64 v[66:67], v[66:67], 0, v[162:163]
	global_load_dwordx4 v[114:117], v[68:69], off offset:256 nt
	global_load_dwordx4 v[122:125], v[68:69], off nt
	global_load_dwordx4 v[118:121], v[66:67], off offset:256 nt
	global_load_dwordx4 v[126:129], v[66:67], off nt
	s_and_b64 vcc, exec, s[0:1]
	v_readlane_b32 s37, v253, 17
	v_readlane_b32 s38, v253, 18
	v_readlane_b32 s39, v253, 19
	v_readlane_b32 s44, v253, 24
	v_readlane_b32 s45, v253, 25
	v_readlane_b32 s46, v253, 26
	v_readlane_b32 s47, v253, 27
	v_readlane_b32 s48, v253, 28
	v_readlane_b32 s49, v253, 29
	v_readlane_b32 s50, v253, 30
	v_readlane_b32 s51, v253, 31
	s_waitcnt lgkmcnt(0)
	s_barrier
	s_cbranch_vccnz .LBB0_851
	v_add_u32_e32 v78, s96, v135
	v_add_u32_e32 v66, 0x11100, v78
	v_add_u32_e32 v67, 0x11180, v78
	v_add_u32_e32 v70, 0x11120, v78
	v_add_u32_e32 v74, 0x11140, v78
	ds_read_b128 v[82:85], v66
	ds_read_b128 v[66:69], v67
	ds_read_b128 v[86:89], v70
	ds_read_b128 v[90:93], v74
	v_add_u32_e32 v70, 0x111a0, v78
	v_add_u32_e32 v74, 0x111c0, v78
	v_add_u32_e32 v79, 0x11160, v78
	v_add_u32_e32 v78, 0x111e0, v78
	ds_read_b128 v[94:97], v79
	ds_read_b128 v[78:81], v78
	ds_read_b128 v[70:73], v70
	ds_read_b128 v[74:77], v74
	v_add_u32_e32 v163, s33, v181
	ds_read_b128 v[204:207], v163
	ds_read_b128 v[212:215], v181 offset:16384
	ds_read_b128 v[216:219], v181 offset:24576
	v_add_u32_e32 v163, s33, v182
	ds_read_b128 v[234:237], v163
	ds_read_b128 v[238:241], v182 offset:16384
	ds_read_b128 v[242:245], v182 offset:24576
	s_waitcnt lgkmcnt(4)
	v_mfma_f32_32x32x16_bf16 v[82:97], v[212:215], v[204:207], v[82:97]
	s_waitcnt lgkmcnt(3)
	v_mfma_f32_32x32x16_bf16 v[66:81], v[216:219], v[204:207], v[66:81]
	v_add_u32_e32 v163, s33, v184
	ds_read_b128 v[204:207], v163
	ds_read_b128 v[212:215], v184 offset:16384
	ds_read_b128 v[216:219], v184 offset:24576
	s_waitcnt lgkmcnt(4)
	v_mfma_f32_32x32x16_bf16 v[82:97], v[238:241], v[234:237], v[82:97]
	s_waitcnt lgkmcnt(3)
	v_mfma_f32_32x32x16_bf16 v[66:81], v[242:245], v[234:237], v[66:81]
	v_add_u32_e32 v163, s33, v185
	ds_read_b128 v[234:237], v163
	ds_read_b128 v[238:241], v185 offset:16384
	ds_read_b128 v[242:245], v185 offset:24576
	s_waitcnt lgkmcnt(4)
	v_mfma_f32_32x32x16_bf16 v[82:97], v[212:215], v[204:207], v[82:97]
	s_waitcnt lgkmcnt(3)
	v_mfma_f32_32x32x16_bf16 v[66:81], v[216:219], v[204:207], v[66:81]
	v_add_u32_e32 v163, s33, v186
	ds_read_b128 v[204:207], v163
	ds_read_b128 v[212:215], v186 offset:16384
	ds_read_b128 v[216:219], v186 offset:24576
	s_waitcnt lgkmcnt(4)
	v_mfma_f32_32x32x16_bf16 v[82:97], v[238:241], v[234:237], v[82:97]
	s_waitcnt lgkmcnt(3)
	v_mfma_f32_32x32x16_bf16 v[66:81], v[242:245], v[234:237], v[66:81]
	v_add_u32_e32 v163, s33, v187
	ds_read_b128 v[234:237], v163
	ds_read_b128 v[238:241], v187 offset:16384
	ds_read_b128 v[242:245], v187 offset:24576
	s_waitcnt lgkmcnt(4)
	v_mfma_f32_32x32x16_bf16 v[82:97], v[212:215], v[204:207], v[82:97]
	s_waitcnt lgkmcnt(3)
; __device__ __forceinline__ int crow(int r, int hi) { return (r & 3) + 8 * (r >> 2) + 4 * hi; }
; __device__ __forceinline__ void qkt(f32x16& p0, f32x16& p1, const char* Ks, const char* Qs, int r32, int hi) {
; #pragma unroll
;     for (int d0 = 0; d0 < 8; ++d0) { const int cb = (d0 * 16 + hi * 8) * 2;
;         const bf16x8 qv = *reinterpret_cast<const bf16x8*>(Qs + KSWZ(r32, cb));
;         const bf16x8 b0 = *reinterpret_cast<const bf16x8*>(Ks + KSWZ(r32, cb));
;         const bf16x8 b1 = *reinterpret_cast<const bf16x8*>(Ks + KSWZ(32 + r32, cb));
;         p0 = __builtin_amdgcn_mfma_f32_32x32x16_bf16(b0, qv, p0, 0, 0, 0);
;         p1 = __builtin_amdgcn_mfma_f32_32x32x16_bf16(b1, qv, p1, 0, 0, 0); }
; }
; template <int MODE, bool SAMPLE>
; __device__ __forceinline__ void attn_unit(const Params& p, char* lds, int b, int h, int qb) {
;     ...
;                 float pmax = p0[0];
; #pragma unroll
;                 for (int r = 1; r < 16; ++r) pmax = fmaxf(pmax, p0[r]);
; #pragma unroll
;                 for (int r = 0; r < 16; ++r) pmax = fmaxf(pmax, p1[r]);
;                 { auto rr = __builtin_amdgcn_permlane32_swap(__float_as_uint(pmax), __float_as_uint(pmax), false, false); pmax = fmaxf(__uint_as_float(rr[0]), __uint_as_float(rr[1])); }
;                 float alpha = 1.f;
;                 if (!__all(pmax - m_reg <= 8.f)) { const float mn = fmaxf(m_reg, pmax); alpha = __builtin_amdgcn_exp2f(m_reg - mn); m_reg = mn; }
;                 float ps = 0.f;
; #pragma unroll
;                 for (int r = 0; r < 16; ++r) { p0[r] = __builtin_amdgcn_exp2f(p0[r] - m_reg); p1[r] = __builtin_amdgcn_exp2f(p1[r] - m_reg); ps += p0[r] + p1[r]; }
;                 { auto rr = __builtin_amdgcn_permlane32_swap(__float_as_uint(ps), __float_as_uint(ps), false, false); ps = __uint_as_float(rr[0]) + __uint_as_float(rr[1]); }
;                 l_reg = l_reg * alpha + ps;
;                 if (__any(alpha < 1.f)) { if (hi == 0) wsc[r32] = alpha; asm volatile("s_waitcnt lgkmcnt(0)" ::: "memory");
; #pragma unroll
;                     for (int d = 0; d < 4; ++d)
; #pragma unroll
;                         for (int r = 0; r < 16; ++r) o[d][r] *= wsc[crow(r, hi)]; }
	v_mfma_f32_32x32x16_bf16 v[66:81], v[216:219], v[204:207], v[66:81]
	v_add_u32_e32 v163, s33, v188
	ds_read_b128 v[204:207], v163
	ds_read_b128 v[212:215], v188 offset:16384
	ds_read_b128 v[216:219], v188 offset:24576
	s_waitcnt lgkmcnt(4)
	v_mfma_f32_32x32x16_bf16 v[82:97], v[238:241], v[234:237], v[82:97]
	s_waitcnt lgkmcnt(3)
	v_mfma_f32_32x32x16_bf16 v[66:81], v[242:245], v[234:237], v[66:81]
	v_add_u32_e32 v163, s33, v189
	ds_read_b128 v[234:237], v163
	ds_read_b128 v[238:241], v189 offset:16384
	ds_read_b128 v[242:245], v189 offset:24576
	s_waitcnt lgkmcnt(4)
	v_mfma_f32_32x32x16_bf16 v[82:97], v[212:215], v[204:207], v[82:97]
	s_waitcnt lgkmcnt(3)
	v_mfma_f32_32x32x16_bf16 v[66:81], v[216:219], v[204:207], v[66:81]
	s_waitcnt lgkmcnt(1)
	v_mfma_f32_32x32x16_bf16 v[82:97], v[238:241], v[234:237], v[82:97]
	s_waitcnt lgkmcnt(0)
	v_mfma_f32_32x32x16_bf16 v[66:81], v[242:245], v[234:237], v[66:81]
	s_nop 1
	s_nop 9
	v_max_f32_e32 v163, v83, v83
	v_max_f32_e32 v203, v82, v82
	v_max_f32_e32 v163, v203, v163
	v_max3_f32 v163, v163, v84, v85
	v_max3_f32 v163, v163, v86, v87
	v_max3_f32 v163, v163, v88, v89
	v_max3_f32 v163, v163, v90, v91
	v_max3_f32 v163, v163, v92, v93
	v_max3_f32 v163, v163, v94, v95
	v_max3_f32 v163, v163, v96, v97
	v_max3_f32 v163, v163, v66, v67
	v_max3_f32 v163, v163, v68, v69
	v_max3_f32 v163, v163, v70, v71
	v_max3_f32 v163, v163, v72, v73
	v_max3_f32 v163, v163, v74, v75
	v_max3_f32 v163, v163, v76, v77
	v_max3_f32 v163, v163, v78, v79
	v_max3_f32 v163, v163, v80, v81
	v_mov_b32_e32 v203, v163
	s_nop 1
	v_permlane32_swap_b32_e32 v163, v203
	v_max_f32_e32 v203, v203, v203
	v_max_f32_e32 v163, v163, v163
	v_max_f32_e32 v163, v163, v203
	v_sub_f32_e32 v203, v163, v161
	v_cmp_ge_f32_e32 vcc, s82, v203
	s_cmp_eq_u64 vcc, exec
	v_max_f32_e32 v203, v161, v161
	s_cselect_b64 vcc, -1, 0
	v_max_f32_e32 v163, v203, v163
	v_sub_f32_e32 v203, v161, v163
	v_cndmask_b32_e32 v161, v163, v161, vcc
	v_sub_f32_e32 v82, v82, v161
	v_sub_f32_e32 v66, v66, v161
	v_exp_f32_e32 v163, v82
	v_exp_f32_e32 v82, v66
	v_exp_f32_e32 v204, v203
	v_sub_f32_e32 v67, v67, v161
	v_sub_f32_e32 v68, v68, v161
	v_add_f32_e32 v66, v163, v82
	v_add_f32_e32 v203, 0, v66
	v_sub_f32_e32 v66, v83, v161
	v_exp_f32_e32 v66, v66
	v_exp_f32_e32 v83, v67
	v_sub_f32_e32 v69, v69, v161
	v_sub_f32_e32 v70, v70, v161
	v_exp_f32_e32 v70, v70
	v_add_f32_e32 v67, v66, v83
	v_add_f32_e32 v203, v67, v203
	v_sub_f32_e32 v67, v84, v161
	v_exp_f32_e32 v67, v67
	v_exp_f32_e32 v84, v68
	v_sub_f32_e32 v71, v71, v161
	v_exp_f32_e32 v71, v71
	v_sub_f32_e32 v72, v72, v161
	v_add_f32_e32 v68, v67, v84
	v_add_f32_e32 v203, v68, v203
	v_sub_f32_e32 v68, v85, v161
	v_exp_f32_e32 v68, v68
	v_exp_f32_e32 v85, v69
	v_exp_f32_e32 v72, v72
	v_sub_f32_e32 v73, v73, v161
	v_exp_f32_e32 v73, v73
	v_add_f32_e32 v69, v68, v85
	v_add_f32_e32 v203, v69, v203
	v_sub_f32_e32 v69, v86, v161
	v_exp_f32_e32 v69, v69
	v_sub_f32_e32 v74, v74, v161
	v_exp_f32_e32 v74, v74
	v_sub_f32_e32 v75, v75, v161
	v_add_f32_e32 v86, v69, v70
	v_add_f32_e32 v203, v86, v203
	v_sub_f32_e32 v86, v87, v161
	v_exp_f32_e32 v86, v86
	v_exp_f32_e32 v75, v75
	v_sub_f32_e32 v76, v76, v161
	v_exp_f32_e32 v76, v76
	v_add_f32_e32 v87, v86, v71
	v_add_f32_e32 v203, v87, v203
	v_sub_f32_e32 v87, v88, v161
	v_exp_f32_e32 v87, v87
	v_sub_f32_e32 v77, v77, v161
	v_exp_f32_e32 v77, v77
	v_sub_f32_e32 v78, v78, v161
	v_add_f32_e32 v88, v87, v72
	v_add_f32_e32 v203, v88, v203
	v_sub_f32_e32 v88, v89, v161
	v_exp_f32_e32 v88, v88
	v_exp_f32_e32 v78, v78
	v_sub_f32_e32 v79, v79, v161
	v_exp_f32_e32 v79, v79
	v_add_f32_e32 v89, v88, v73
	v_add_f32_e32 v203, v89, v203
	v_sub_f32_e32 v89, v90, v161
	v_exp_f32_e32 v89, v89
	v_sub_f32_e32 v80, v80, v161
	v_exp_f32_e32 v80, v80
	v_sub_f32_e32 v81, v81, v161
	v_add_f32_e32 v90, v89, v74
	v_add_f32_e32 v203, v90, v203
	v_sub_f32_e32 v90, v91, v161
	v_exp_f32_e32 v90, v90
	v_exp_f32_e32 v81, v81
	v_add_f32_e32 v91, v90, v75
	v_add_f32_e32 v203, v91, v203
	v_sub_f32_e32 v91, v92, v161
	v_exp_f32_e32 v91, v91
	s_nop 0
	v_add_f32_e32 v92, v91, v76
	v_add_f32_e32 v203, v92, v203
	v_sub_f32_e32 v92, v93, v161
	v_exp_f32_e32 v92, v92
	s_nop 0
	v_add_f32_e32 v93, v92, v77
	v_add_f32_e32 v203, v93, v203
	v_sub_f32_e32 v93, v94, v161
	v_exp_f32_e32 v93, v93
	s_nop 0
	v_add_f32_e32 v94, v93, v78
	v_add_f32_e32 v203, v94, v203
	v_sub_f32_e32 v94, v95, v161
	v_exp_f32_e32 v94, v94
	s_nop 0
	v_add_f32_e32 v95, v94, v79
	v_add_f32_e32 v203, v95, v203
	v_sub_f32_e32 v95, v96, v161
	v_exp_f32_e32 v95, v95
	s_nop 0
	v_add_f32_e32 v96, v95, v80
	v_add_f32_e32 v203, v96, v203
	v_sub_f32_e32 v96, v97, v161
	v_exp_f32_e32 v96, v96
	s_nop 0
	v_add_f32_e32 v97, v96, v81
	v_add_f32_e32 v203, v97, v203
	v_cndmask_b32_e64 v97, v204, 1.0, vcc
	v_mov_b32_e32 v204, v203
	s_nop 1
	v_permlane32_swap_b32_e32 v203, v204
	v_cmp_gt_f32_e32 vcc, 1.0, v97
	s_cbranch_vccz .LBB0_850
	s_and_saveexec_b64 s[2:3], s[12:13]
	ds_write_b32 v147, v97
	s_or_b64 exec, exec, s[2:3]
	s_waitcnt lgkmcnt(0)
	ds_read_b128 v[206:209], v149 offset:96
	ds_read_b128 v[212:215], v149 offset:64
	ds_read_b128 v[216:219], v149 offset:32
	ds_read_b128 v[220:223], v149
	s_waitcnt lgkmcnt(3)
	v_pk_mul_f32 v[64:65], v[64:65], v[208:209]
	s_waitcnt lgkmcnt(2)
	v_pk_mul_f32 v[60:61], v[60:61], v[214:215]
	s_waitcnt lgkmcnt(1)
	v_pk_mul_f32 v[56:57], v[56:57], v[218:219]
	s_waitcnt lgkmcnt(0)
	v_pk_mul_f32 v[52:53], v[52:53], v[222:223]
	v_pk_mul_f32 v[62:63], v[62:63], v[206:207]
	v_pk_mul_f32 v[58:59], v[58:59], v[212:213]
	v_pk_mul_f32 v[54:55], v[54:55], v[216:217]
	v_pk_mul_f32 v[50:51], v[50:51], v[220:221]
	v_pk_mul_f32 v[48:49], v[48:49], v[208:209]
	v_pk_mul_f32 v[44:45], v[44:45], v[214:215]
	v_pk_mul_f32 v[40:41], v[40:41], v[218:219]
	v_pk_mul_f32 v[36:37], v[36:37], v[222:223]
	v_pk_mul_f32 v[46:47], v[46:47], v[206:207]
	v_pk_mul_f32 v[42:43], v[42:43], v[212:213]
	v_pk_mul_f32 v[38:39], v[38:39], v[216:217]
	v_pk_mul_f32 v[34:35], v[34:35], v[220:221]
	v_pk_mul_f32 v[32:33], v[32:33], v[208:209]
	v_pk_mul_f32 v[28:29], v[28:29], v[214:215]
	v_pk_mul_f32 v[24:25], v[24:25], v[218:219]
	v_pk_mul_f32 v[20:21], v[20:21], v[222:223]
	v_pk_mul_f32 v[30:31], v[30:31], v[206:207]
	v_pk_mul_f32 v[26:27], v[26:27], v[212:213]
	v_pk_mul_f32 v[22:23], v[22:23], v[216:217]
	v_pk_mul_f32 v[18:19], v[18:19], v[220:221]
	v_pk_mul_f32 v[16:17], v[16:17], v[208:209]
	v_pk_mul_f32 v[12:13], v[12:13], v[214:215]
	v_pk_mul_f32 v[8:9], v[8:9], v[218:219]
	v_pk_mul_f32 v[4:5], v[4:5], v[222:223]
	v_pk_mul_f32 v[14:15], v[14:15], v[206:207]
	v_pk_mul_f32 v[10:11], v[10:11], v[212:213]
	v_pk_mul_f32 v[6:7], v[6:7], v[216:217]
	v_pk_mul_f32 v[2:3], v[2:3], v[220:221]

; __device__ __forceinline__ int crow(int r, int hi) { return (r & 3) + 8 * (r >> 2) + 4 * hi; }
; __device__ __forceinline__ void qkt(f32x16& p0, f32x16& p1, const char* Ks, const char* Qs, int r32, int hi) {
; #pragma unroll
;     for (int d0 = 0; d0 < 8; ++d0) { const int cb = (d0 * 16 + hi * 8) * 2;
;         const bf16x8 qv = *reinterpret_cast<const bf16x8*>(Qs + KSWZ(r32, cb));
;         const bf16x8 b0 = *reinterpret_cast<const bf16x8*>(Ks + KSWZ(r32, cb));
;         const bf16x8 b1 = *reinterpret_cast<const bf16x8*>(Ks + KSWZ(32 + r32, cb));
;         p0 = __builtin_amdgcn_mfma_f32_32x32x16_bf16(b0, qv, p0, 0, 0, 0);
;         p1 = __builtin_amdgcn_mfma_f32_32x32x16_bf16(b1, qv, p1, 0, 0, 0); }
; }
; template <int MODE, bool SAMPLE>
; __device__ __forceinline__ void attn_unit(const Params& p, char* lds, int b, int h, int qb) {
;     ...
;             const char* Kt = K_lds + buf * 16384; const int vb = vb0 + buf * 16384;
;             f32x16 p0, p1; bf16x8 pa0, pa1, pa2, pa3;
;             if (MODE == 0) {
;                 const float* bt = biasL + j * 64 + 4 * hi;
; #pragma unroll
;                 for (int g = 0; g < 4; ++g) { const f32x4 a = *(const f32x4*)(bt + 8 * g), c = *(const f32x4*)(bt + 32 + 8 * g);
; #pragma unroll
;                     for (int i = 0; i < 4; ++i) { p0[4 * g + i] = a[i]; p1[4 * g + i] = c[i]; } }
;                 qkt(p0, p1, Kt, Qs, r32, hi);
;                 if (j == jd) {
; #pragma unroll
;                     for (int r = 0; r < 16; ++r) { const int kp = j * 64 + crow(r, hi); if (kp > qpos) p0[r] = -1e30f; if (kp + 32 > qpos) p1[r] = -1e30f; } }
.LBB0_853:
	s_and_b64 vcc, exec, s[0:1]
	v_add_u32_e32 v203, 0, v181
	v_add_u32_e32 v204, 0, v182
	v_add_u32_e32 v205, 0, v184
	v_add_u32_e32 v206, 0, v185
	v_add_u32_e32 v207, 0, v186
	v_add_u32_e32 v208, 0, v187
	v_add_u32_e32 v209, 0, v188
	v_add_u32_e32 v210, 0, v189
	s_waitcnt lgkmcnt(0)
	s_barrier
	s_cbranch_vccnz .LBB0_843
	v_add_u32_e32 v94, s96, v135
	v_add_u32_e32 v66, 0x11000, v94
	v_add_u32_e32 v70, 0x11080, v94
	ds_read_b128 v[66:69], v66
	ds_read_b128 v[82:85], v70
	v_add_u32_e32 v70, 0x11020, v94
	v_add_u32_e32 v74, 0x11040, v94
	v_add_u32_e32 v78, 0x11060, v94
	ds_read_b128 v[70:73], v70
	ds_read_b128 v[74:77], v74
	ds_read_b128 v[78:81], v78
	v_add_u32_e32 v86, 0x110a0, v94
	v_add_u32_e32 v95, 0x110c0, v94
	v_add_u32_e32 v94, 0x110e0, v94
	ds_read_b128 v[86:89], v86
	ds_read_b128 v[90:93], v95
	ds_read_b128 v[94:97], v94
	s_cmp_lg_u32 s96, 0
	v_add_u32_e32 v163, s33, v181
	ds_read_b128 v[216:219], v163
	ds_read_b128 v[212:215], v203
	ds_read_b128 v[246:249], v203 offset:8192
	v_add_u32_e32 v163, s33, v182
	ds_read_b128 v[234:237], v163
	ds_read_b128 v[238:241], v204
	ds_read_b128 v[242:245], v204 offset:8192
	s_waitcnt lgkmcnt(4)
	v_mfma_f32_32x32x16_bf16 v[66:81], v[212:215], v[216:219], v[66:81]
	s_waitcnt lgkmcnt(3)
	v_mfma_f32_32x32x16_bf16 v[82:97], v[246:249], v[216:219], v[82:97]
	v_add_u32_e32 v163, s33, v184
	ds_read_b128 v[216:219], v163
	ds_read_b128 v[212:215], v205
	ds_read_b128 v[246:249], v205 offset:8192
	s_waitcnt lgkmcnt(4)
	v_mfma_f32_32x32x16_bf16 v[66:81], v[238:241], v[234:237], v[66:81]
	s_waitcnt lgkmcnt(3)
	v_mfma_f32_32x32x16_bf16 v[82:97], v[242:245], v[234:237], v[82:97]
	v_add_u32_e32 v163, s33, v185
	ds_read_b128 v[234:237], v163
	ds_read_b128 v[238:241], v206
	ds_read_b128 v[242:245], v206 offset:8192
	s_waitcnt lgkmcnt(4)
	v_mfma_f32_32x32x16_bf16 v[66:81], v[212:215], v[216:219], v[66:81]
	s_waitcnt lgkmcnt(3)
	v_mfma_f32_32x32x16_bf16 v[82:97], v[246:249], v[216:219], v[82:97]
	v_add_u32_e32 v163, s33, v186
	ds_read_b128 v[216:219], v163
	ds_read_b128 v[212:215], v207
	ds_read_b128 v[246:249], v207 offset:8192
	s_waitcnt lgkmcnt(4)
	v_mfma_f32_32x32x16_bf16 v[66:81], v[238:241], v[234:237], v[66:81]
	s_waitcnt lgkmcnt(3)
	v_mfma_f32_32x32x16_bf16 v[82:97], v[242:245], v[234:237], v[82:97]
	v_add_u32_e32 v163, s33, v187
	ds_read_b128 v[234:237], v163
	ds_read_b128 v[238:241], v208
	ds_read_b128 v[242:245], v208 offset:8192
	s_waitcnt lgkmcnt(4)
	v_mfma_f32_32x32x16_bf16 v[66:81], v[212:215], v[216:219], v[66:81]
	s_waitcnt lgkmcnt(3)
	v_mfma_f32_32x32x16_bf16 v[82:97], v[246:249], v[216:219], v[82:97]
	v_add_u32_e32 v163, s33, v188
	ds_read_b128 v[216:219], v163
	ds_read_b128 v[212:215], v209
	ds_read_b128 v[246:249], v209 offset:8192
	s_waitcnt lgkmcnt(4)
	v_mfma_f32_32x32x16_bf16 v[66:81], v[238:241], v[234:237], v[66:81]
	s_waitcnt lgkmcnt(3)
	v_mfma_f32_32x32x16_bf16 v[82:97], v[242:245], v[234:237], v[82:97]
	v_add_u32_e32 v163, s33, v189
	ds_read_b128 v[234:237], v163
	ds_read_b128 v[238:241], v210
	ds_read_b128 v[242:245], v210 offset:8192
	s_waitcnt lgkmcnt(4)
	v_mfma_f32_32x32x16_bf16 v[66:81], v[212:215], v[216:219], v[66:81]
	s_waitcnt lgkmcnt(3)
	v_mfma_f32_32x32x16_bf16 v[82:97], v[246:249], v[216:219], v[82:97]
	s_waitcnt lgkmcnt(1)
	v_mfma_f32_32x32x16_bf16 v[66:81], v[238:241], v[234:237], v[66:81]
	s_waitcnt lgkmcnt(0)
	v_mfma_f32_32x32x16_bf16 v[82:97], v[242:245], v[234:237], v[82:97]
	s_nop 1
	s_cbranch_scc1 .LBB0_856
	s_nop 10
	v_mov_b32_e32 v82, 0xf149f2ca
	v_cndmask_b32_e64 v74, v66, v82, s[20:21]
	v_cndmask_b32_e64 v66, v74, v66, s[22:23]
	v_cndmask_b32_e64 v67, v82, v67, s[22:23]
	v_cndmask_b32_e64 v68, v68, v82, s[24:25]
	v_cndmask_b32_e64 v69, v69, v82, s[26:27]
	v_cndmask_b32_e64 v70, v70, v82, s[28:29]
	v_cndmask_b32_e64 v71, v71, v82, s[30:31]
	v_cndmask_b32_e64 v72, v72, v82, s[34:35]
	v_cndmask_b32_e64 v73, v73, v82, s[18:19]
	v_mov_b32_e32 v83, v82
	v_mov_b32_e32 v84, v82
	v_mov_b32_e32 v85, v82
	v_mov_b32_e32 v86, v82
	v_mov_b32_e32 v87, v82
	v_mov_b32_e32 v88, v82
	v_mov_b32_e32 v89, v82
	v_mov_b32_e32 v90, v82
	v_mov_b32_e32 v91, v82
	v_mov_b32_e32 v92, v82
	v_mov_b32_e32 v93, v82
	v_mov_b32_e32 v94, v82
	v_mov_b32_e32 v95, v82
	v_mov_b32_e32 v96, v82
	v_mov_b32_e32 v97, v82
	v_mov_b32_e32 v74, v82
	v_mov_b32_e32 v75, v82
	v_mov_b32_e32 v76, v82
	v_mov_b32_e32 v77, v82
	v_mov_b32_e32 v78, v82
	v_mov_b32_e32 v79, v82
	v_mov_b32_e32 v80, v82
	v_mov_b32_e32 v81, v82
